# unit boundary: hipcc's s_waitcnt vmcnt(0) before the first K-loop trip removed (in-loop counted waits drain the epilogue stores), on top of peel0+gsz8
# speedup vs baseline: 1.0016x; 1.0016x over previous
; #define PG8_STAGE(bufoff, gbase, voff) do { _Pragma("unroll") for (int _i = 0; _i < 2; ++_i) \
;         __builtin_amdgcn_global_load_lds((const unsigned*)((const char*)(gbase) + (voff)[_i]), (PG8_LAS unsigned*)(lds + (bufoff) + ldsw + _i * 8192), 16, 0, 0); } while (0)
; #define PG8_LDA(dst, b, h) do { _Pragma("unroll") for (int m = 0; m < 4; ++m) _Pragma("unroll") for (int k = 0; k < 2; ++k) dst[m][k] = *(const PG8_LAS bf16x8*)(lds + PG8_SA(b, h) + aoff + m * 2048 + k * 1024); } while (0)
; #define PG8_LDB(dst, b, h) do { _Pragma("unroll") for (int n = 0; n < 2; ++n) _Pragma("unroll") for (int k = 0; k < 2; ++k) dst[n][k] = *(const PG8_LAS bf16x8*)(lds + PG8_SB(b, h) + boff + n * 2048 + k * 1024); } while (0)
; #define PG8_MMA(ai, bj, At, Bt) do { __builtin_amdgcn_s_setprio(1); _Pragma("unroll") for (int m = 0; m < 4; ++m) _Pragma("unroll") for (int n = 0; n < 2; ++n) _Pragma("unroll") for (int k = 0; k < 2; ++k) \
;         acc[ai][bj][m][n] = __builtin_amdgcn_mfma_f32_16x16x32_bf16(Bt[n][k], At[m][k], acc[ai][bj][m][n], 0, 0, 0); __builtin_amdgcn_s_setprio(0); } while (0)
; #define PG8_WAIT_V(n) asm volatile("s_waitcnt vmcnt(" #n ")" ::: "memory")
; #define PG8_WAIT_L(n) asm volatile("s_waitcnt lgkmcnt(" #n ")" ::: "memory")
; template <class Epi, class Sched, bool ALIGN_EPI = false, bool SP2 = false>
; __device__ __forceinline__ void gemm_phase(PG8_LAS unsigned char* lds, const Gemm g, const Sched& S, const Epi& E) {
;     ...
;             const bool last = (t == nt - 2);
;             const char* a1 = cA + (size_t)(t + 1) * kstep;
;             const char* a2 = last ? nA : cA + (size_t)(t + 2) * kstep; const char* b2 = last ? nB : cB + (size_t)(t + 2) * kstep;
;             const char* a3 = a2 + kstep; const char* b3 = b2 + kstep;
;             if (last && has_next) S.a_ready(nxt);
;             if constexpr (SP2) {
;             PG8_LDB(B0, 0, 0); PG8_LDB(B1, 0, 1); PG8_SCHED; PG8_LDA(At, 0, 0); PG8_STAGE(PG8_SA(1, 1), a1 + hstep, voffA);
;             PG8_WAIT_V(8); PG8_WAIT_L(0); PG8_BAR; PG8_MMA(0, 0, At, B0); PG8_MMA(0, 1, At, B1); PG8_BAR; PG8_SCHED;
;             PG8_LDA(At, 0, 1); PG8_STAGE(PG8_SB(0, 0), b2, voffB); PG8_STAGE(PG8_SB(0, 1), b2 + hstep, voffB); PG8_STAGE(PG8_SA(0, 0), a2, voffA);
;             PG8_WAIT_V(8); PG8_WAIT_L(0); PG8_BAR; PG8_MMA(1, 0, At, B0); PG8_MMA(1, 1, At, B1); PG8_BAR; PG8_SCHED;
.LBB0_164:
	s_ashr_i32 s47, s46, 31
	s_lshl_b64 s[58:59], s[46:47], 20
	s_add_u32 s74, s12, s58
	s_addc_u32 s75, s13, s59
	s_and_b64 s[58:59], s[40:41], exec
	s_cselect_b32 s47, s75, s43
	s_cselect_b32 s55, s74, s42
	s_ashr_i32 s45, s44, 31
	s_lshl_b64 s[58:59], s[44:45], 20
	v_readlane_b32 s68, v255, 52
	v_readlane_b32 s69, v255, 53
	s_add_u32 s76, s68, s58
	s_addc_u32 s77, s69, s59
	s_and_b64 s[58:59], s[40:41], exec
	s_cselect_b32 s45, s77, s79
	s_cselect_b32 s58, s76, s78
	s_add_u32 s42, s42, 0x80080
	s_addc_u32 s43, s43, 0
	s_add_u32 s59, s78, 0x100
	v_mov_b32_e32 v0, 0
	s_addc_u32 s63, s79, 0
	s_mov_b32 s71, -2
	s_add_u32 s68, s42, 0xfff80080
	s_addc_u32 s69, s43, -1
	s_add_i32 s82, 0, 0x10000
	s_cmp_eq_u32 s71, 28
	s_cselect_b32 s81, s47, s69
	s_cselect_b32 s80, s55, s68
	v_add_u32_e32 v144, s82, v147
	s_cselect_b32 s79, s45, s63
	s_cselect_b32 s78, s58, s59
	s_add_i32 s83, 0, 0x14000
	ds_read_b128 v[140:143], v144
	ds_read_b128 v[156:159], v144 offset:1024
	ds_read_b128 v[160:163], v144 offset:2048
	ds_read_b128 v[164:167], v144 offset:3072
	v_add_u32_e32 v144, s83, v147
	ds_read_b128 v[168:171], v144
	ds_read_b128 v[172:175], v144 offset:1024
	ds_read_b128 v[192:195], v144 offset:2048
	ds_read_b128 v[196:199], v144 offset:3072
	v_lshl_add_u64 v[150:151], s[42:43], 0, v[136:137]
	s_add_i32 m0, s14, 0xc000
	ds_read_b128 v[200:203], v149
	ds_read_b128 v[204:207], v149 offset:1024
	ds_read_b128 v[208:211], v149 offset:2048
	ds_read_b128 v[212:215], v149 offset:3072
	ds_read_b128 v[216:219], v149 offset:4096
	ds_read_b128 v[220:223], v149 offset:5120
	ds_read_b128 v[224:227], v149 offset:6144
	ds_read_b128 v[228:231], v149 offset:7168
	global_load_lds_dwordx4 v[150:151], off
	v_lshl_add_u64 v[150:151], s[42:43], 0, v[138:139]
	s_add_i32 m0, s14, 0xe000
	s_nop 0
	global_load_lds_dwordx4 v[150:151], off
	s_waitcnt vmcnt(8)
	s_waitcnt lgkmcnt(0)
	s_setprio 1
	s_barrier
	v_mfma_f32_16x16x32_bf16 v[124:127], v[140:143], v[200:203], 0
	v_mfma_f32_16x16x32_bf16 v[120:123], v[160:163], v[200:203], 0
	v_mfma_f32_16x16x32_bf16 v[108:111], v[140:143], v[208:211], 0
	v_mfma_f32_16x16x32_bf16 v[104:107], v[160:163], v[208:211], 0
	v_mfma_f32_16x16x32_bf16 v[92:95], v[140:143], v[216:219], 0
	v_mfma_f32_16x16x32_bf16 v[88:91], v[160:163], v[216:219], 0
	v_mfma_f32_16x16x32_bf16 v[76:79], v[140:143], v[224:227], 0
	v_mfma_f32_16x16x32_bf16 v[72:75], v[160:163], v[224:227], 0
	v_mfma_f32_16x16x32_bf16 v[124:127], v[156:159], v[204:207], v[124:127]
	v_mfma_f32_16x16x32_bf16 v[120:123], v[164:167], v[204:207], v[120:123]
	v_mfma_f32_16x16x32_bf16 v[108:111], v[156:159], v[212:215], v[108:111]
	v_mfma_f32_16x16x32_bf16 v[104:107], v[164:167], v[212:215], v[104:107]
	v_mfma_f32_16x16x32_bf16 v[92:95], v[156:159], v[220:223], v[92:95]
	v_mfma_f32_16x16x32_bf16 v[88:91], v[164:167], v[220:223], v[88:91]
	v_mfma_f32_16x16x32_bf16 v[76:79], v[156:159], v[228:231], v[76:79]
	v_mfma_f32_16x16x32_bf16 v[72:75], v[164:167], v[228:231], v[72:75]
	v_mfma_f32_16x16x32_bf16 v[116:119], v[168:171], v[200:203], 0
	v_mfma_f32_16x16x32_bf16 v[112:115], v[192:195], v[200:203], 0
	v_mfma_f32_16x16x32_bf16 v[100:103], v[168:171], v[208:211], 0
	v_mfma_f32_16x16x32_bf16 v[96:99], v[192:195], v[208:211], 0
	v_mfma_f32_16x16x32_bf16 v[84:87], v[168:171], v[216:219], 0
	v_mfma_f32_16x16x32_bf16 v[80:83], v[192:195], v[216:219], 0
	v_mfma_f32_16x16x32_bf16 v[68:71], v[168:171], v[224:227], 0
	v_mfma_f32_16x16x32_bf16 v[64:67], v[192:195], v[224:227], 0
	v_mfma_f32_16x16x32_bf16 v[116:119], v[172:175], v[204:207], v[116:119]
	v_mfma_f32_16x16x32_bf16 v[112:115], v[196:199], v[204:207], v[112:115]
	v_mfma_f32_16x16x32_bf16 v[100:103], v[172:175], v[212:215], v[100:103]
	v_mfma_f32_16x16x32_bf16 v[96:99], v[196:199], v[212:215], v[96:99]
	v_mfma_f32_16x16x32_bf16 v[84:87], v[172:175], v[220:223], v[84:87]
	v_mfma_f32_16x16x32_bf16 v[80:83], v[196:199], v[220:223], v[80:83]
	v_mfma_f32_16x16x32_bf16 v[68:71], v[172:175], v[228:231], v[68:71]
	v_mfma_f32_16x16x32_bf16 v[64:67], v[196:199], v[228:231], v[64:67]
	s_barrier
	s_setprio 0
	s_add_i32 s68, s82, s0
	v_lshl_add_u64 v[150:151], s[78:79], 0, v[152:153]
	s_mov_b32 m0, s68
	ds_read_b128 v[200:203], v149 offset:16384
	ds_read_b128 v[204:207], v149 offset:17408
	ds_read_b128 v[208:211], v149 offset:18432
	ds_read_b128 v[212:215], v149 offset:19456
	ds_read_b128 v[216:219], v149 offset:20480
	ds_read_b128 v[220:223], v149 offset:21504
	ds_read_b128 v[224:227], v149 offset:22528
	ds_read_b128 v[228:231], v149 offset:23552
	global_load_lds_dwordx4 v[150:151], off
	s_add_i32 m0, s68, 0x2000
	s_add_u32 s68, s78, 0x80000
	v_lshl_add_u64 v[182:183], s[78:79], 0, v[128:129]
	s_addc_u32 s69, s79, 0
	s_add_i32 s82, s83, s0
	global_load_lds_dwordx4 v[182:183], off
	v_lshl_add_u64 v[184:185], s[68:69], 0, v[152:153]
	s_mov_b32 m0, s82
	v_lshl_add_u64 v[188:189], s[80:81], 0, v[130:131]
	global_load_lds_dwordx4 v[184:185], off
	v_lshl_add_u64 v[184:185], s[68:69], 0, v[128:129]
	s_add_i32 m0, s82, 0x2000
	s_nop 0
	global_load_lds_dwordx4 v[184:185], off
	v_lshl_add_u64 v[184:185], s[80:81], 0, v[132:133]
	s_mov_b32 m0, s14
	s_nop 0
	global_load_lds_dwordx4 v[184:185], off
	s_mov_b32 m0, s15
	s_nop 0
	global_load_lds_dwordx4 v[188:189], off
	s_waitcnt vmcnt(8)
	s_waitcnt lgkmcnt(0)
	s_setprio 1
	s_barrier
; #define PG8_STAGE(bufoff, gbase, voff) do { _Pragma("unroll") for (int _i = 0; _i < 2; ++_i) \
;         __builtin_amdgcn_global_load_lds((const unsigned*)((const char*)(gbase) + (voff)[_i]), (PG8_LAS unsigned*)(lds + (bufoff) + ldsw + _i * 8192), 16, 0, 0); } while (0)
; #define PG8_LDA(dst, b, h) do { _Pragma("unroll") for (int m = 0; m < 4; ++m) _Pragma("unroll") for (int k = 0; k < 2; ++k) dst[m][k] = *(const PG8_LAS bf16x8*)(lds + PG8_SA(b, h) + aoff + m * 2048 + k * 1024); } while (0)
; #define PG8_LDB(dst, b, h) do { _Pragma("unroll") for (int n = 0; n < 2; ++n) _Pragma("unroll") for (int k = 0; k < 2; ++k) dst[n][k] = *(const PG8_LAS bf16x8*)(lds + PG8_SB(b, h) + boff + n * 2048 + k * 1024); } while (0)
; #define PG8_MMA(ai, bj, At, Bt) do { __builtin_amdgcn_s_setprio(1); _Pragma("unroll") for (int m = 0; m < 4; ++m) _Pragma("unroll") for (int n = 0; n < 2; ++n) _Pragma("unroll") for (int k = 0; k < 2; ++k) \
;         acc[ai][bj][m][n] = __builtin_amdgcn_mfma_f32_16x16x32_bf16(Bt[n][k], At[m][k], acc[ai][bj][m][n], 0, 0, 0); __builtin_amdgcn_s_setprio(0); } while (0)
; #define PG8_WAIT_V(n) asm volatile("s_waitcnt vmcnt(" #n ")" ::: "memory")
; #define PG8_WAIT_L(n) asm volatile("s_waitcnt lgkmcnt(" #n ")" ::: "memory")
; #define PG8_BAR __builtin_amdgcn_s_barrier()
; #define PG8_SCHED __builtin_amdgcn_sched_barrier(0)
; template <class Epi, class Sched, bool ALIGN_EPI = false, bool SP2 = false>
; __device__ __forceinline__ void gemm_phase(PG8_LAS unsigned char* lds, const Gemm g, const Sched& S, const Epi& E) {
;     ...
;             PG8_WAIT_V(8); PG8_WAIT_L(0); PG8_BAR; PG8_MMA(1, 0, At, B0); PG8_MMA(1, 1, At, B1); PG8_BAR; PG8_SCHED;
;             PG8_LDB(B0, 1, 0); PG8_LDB(B1, 1, 1); PG8_SCHED; PG8_LDA(At, 1, 0); PG8_STAGE(PG8_SA(0, 1), a2 + hstep, voffA);
;             PG8_WAIT_V(8); PG8_WAIT_L(0); PG8_BAR; PG8_MMA(0, 0, At, B0); PG8_MMA(0, 1, At, B1); PG8_BAR; PG8_SCHED;
;             PG8_LDA(At, 1, 1); PG8_STAGE(PG8_SB(1, 0), b3, voffB); PG8_STAGE(PG8_SB(1, 1), b3 + hstep, voffB); PG8_STAGE(PG8_SA(1, 0), a3, voffA);
	v_mfma_f32_16x16x32_bf16 v[60:63], v[140:143], v[200:203], 0
	v_mfma_f32_16x16x32_bf16 v[56:59], v[160:163], v[200:203], 0
	v_mfma_f32_16x16x32_bf16 v[44:47], v[140:143], v[208:211], 0
	v_mfma_f32_16x16x32_bf16 v[40:43], v[160:163], v[208:211], 0
	v_mfma_f32_16x16x32_bf16 v[28:31], v[140:143], v[216:219], 0
	v_mfma_f32_16x16x32_bf16 v[24:27], v[160:163], v[216:219], 0
	v_mfma_f32_16x16x32_bf16 v[12:15], v[140:143], v[224:227], 0
	v_mfma_f32_16x16x32_bf16 v[8:11], v[160:163], v[224:227], 0
	v_mfma_f32_16x16x32_bf16 v[60:63], v[156:159], v[204:207], v[60:63]
	v_mfma_f32_16x16x32_bf16 v[56:59], v[164:167], v[204:207], v[56:59]
	v_mfma_f32_16x16x32_bf16 v[44:47], v[156:159], v[212:215], v[44:47]
	v_mfma_f32_16x16x32_bf16 v[40:43], v[164:167], v[212:215], v[40:43]
	v_mfma_f32_16x16x32_bf16 v[28:31], v[156:159], v[220:223], v[28:31]
	v_mfma_f32_16x16x32_bf16 v[24:27], v[164:167], v[220:223], v[24:27]
	v_mfma_f32_16x16x32_bf16 v[12:15], v[156:159], v[228:231], v[12:15]
	v_mfma_f32_16x16x32_bf16 v[8:11], v[164:167], v[228:231], v[8:11]
	v_mfma_f32_16x16x32_bf16 v[52:55], v[168:171], v[200:203], 0
	v_mfma_f32_16x16x32_bf16 v[48:51], v[192:195], v[200:203], 0
	v_mfma_f32_16x16x32_bf16 v[36:39], v[168:171], v[208:211], 0
	v_mfma_f32_16x16x32_bf16 v[32:35], v[192:195], v[208:211], 0
	v_mfma_f32_16x16x32_bf16 v[20:23], v[168:171], v[216:219], 0
	v_mfma_f32_16x16x32_bf16 v[16:19], v[192:195], v[216:219], 0
	v_mfma_f32_16x16x32_bf16 v[4:7], v[168:171], v[224:227], 0
	v_mfma_f32_16x16x32_bf16 v[0:3], v[192:195], v[224:227], 0
	v_mfma_f32_16x16x32_bf16 v[52:55], v[172:175], v[204:207], v[52:55]
	v_mfma_f32_16x16x32_bf16 v[48:51], v[196:199], v[204:207], v[48:51]
	v_mfma_f32_16x16x32_bf16 v[36:39], v[172:175], v[212:215], v[36:39]
	v_mfma_f32_16x16x32_bf16 v[32:35], v[196:199], v[212:215], v[32:35]
	v_mfma_f32_16x16x32_bf16 v[20:23], v[172:175], v[220:223], v[20:23]
	v_mfma_f32_16x16x32_bf16 v[16:19], v[196:199], v[220:223], v[16:19]
	v_mfma_f32_16x16x32_bf16 v[4:7], v[172:175], v[228:231], v[4:7]
	v_mfma_f32_16x16x32_bf16 v[0:3], v[196:199], v[228:231], v[0:3]
	s_barrier
	s_setprio 0
	v_add_u32_e32 v144, s93, v147
	s_add_i32 s82, 0, 0x1c000
	ds_read_b128 v[140:143], v144
	ds_read_b128 v[156:159], v144 offset:1024
	ds_read_b128 v[160:163], v144 offset:2048
	ds_read_b128 v[164:167], v144 offset:3072
	v_add_u32_e32 v144, s82, v147
	ds_read_b128 v[168:171], v144
	ds_read_b128 v[172:175], v144 offset:1024
	ds_read_b128 v[192:195], v144 offset:2048
	ds_read_b128 v[196:199], v144 offset:3072
	s_add_u32 s68, s80, 0x80000
	s_addc_u32 s69, s81, 0
	s_mov_b32 m0, s16
	v_lshl_add_u64 v[190:191], s[68:69], 0, v[132:133]
	ds_read_b128 v[200:203], v149 offset:32768
	ds_read_b128 v[204:207], v149 offset:33792
	ds_read_b128 v[208:211], v149 offset:34816
	ds_read_b128 v[212:215], v149 offset:35840
	ds_read_b128 v[216:219], v149 offset:36864
	ds_read_b128 v[220:223], v149 offset:37888
	ds_read_b128 v[224:227], v149 offset:38912
	ds_read_b128 v[228:231], v149 offset:39936
	global_load_lds_dwordx4 v[190:191], off
	v_lshl_add_u64 v[190:191], s[68:69], 0, v[130:131]
	s_mov_b32 m0, s17
	s_nop 0
	global_load_lds_dwordx4 v[190:191], off
	s_waitcnt vmcnt(8)
	s_waitcnt lgkmcnt(0)
	s_setprio 1
	s_barrier
	v_mfma_f32_16x16x32_bf16 v[124:127], v[140:143], v[200:203], v[124:127]
	v_mfma_f32_16x16x32_bf16 v[120:123], v[160:163], v[200:203], v[120:123]
	v_mfma_f32_16x16x32_bf16 v[108:111], v[140:143], v[208:211], v[108:111]
	v_mfma_f32_16x16x32_bf16 v[104:107], v[160:163], v[208:211], v[104:107]
	v_mfma_f32_16x16x32_bf16 v[92:95], v[140:143], v[216:219], v[92:95]
	v_mfma_f32_16x16x32_bf16 v[88:91], v[160:163], v[216:219], v[88:91]
	v_mfma_f32_16x16x32_bf16 v[76:79], v[140:143], v[224:227], v[76:79]
	v_mfma_f32_16x16x32_bf16 v[72:75], v[160:163], v[224:227], v[72:75]
	v_mfma_f32_16x16x32_bf16 v[124:127], v[156:159], v[204:207], v[124:127]
	v_mfma_f32_16x16x32_bf16 v[120:123], v[164:167], v[204:207], v[120:123]
	v_mfma_f32_16x16x32_bf16 v[108:111], v[156:159], v[212:215], v[108:111]
	v_mfma_f32_16x16x32_bf16 v[104:107], v[164:167], v[212:215], v[104:107]
	v_mfma_f32_16x16x32_bf16 v[92:95], v[156:159], v[220:223], v[92:95]
	v_mfma_f32_16x16x32_bf16 v[88:91], v[164:167], v[220:223], v[88:91]
	v_mfma_f32_16x16x32_bf16 v[76:79], v[156:159], v[228:231], v[76:79]
	v_mfma_f32_16x16x32_bf16 v[72:75], v[164:167], v[228:231], v[72:75]
	v_mfma_f32_16x16x32_bf16 v[116:119], v[168:171], v[200:203], v[116:119]
	v_mfma_f32_16x16x32_bf16 v[112:115], v[192:195], v[200:203], v[112:115]
	v_mfma_f32_16x16x32_bf16 v[100:103], v[168:171], v[208:211], v[100:103]
	v_mfma_f32_16x16x32_bf16 v[96:99], v[192:195], v[208:211], v[96:99]
	v_mfma_f32_16x16x32_bf16 v[84:87], v[168:171], v[216:219], v[84:87]
	v_mfma_f32_16x16x32_bf16 v[80:83], v[192:195], v[216:219], v[80:83]
	v_mfma_f32_16x16x32_bf16 v[68:71], v[168:171], v[224:227], v[68:71]
	v_mfma_f32_16x16x32_bf16 v[64:67], v[192:195], v[224:227], v[64:67]
	v_mfma_f32_16x16x32_bf16 v[116:119], v[172:175], v[204:207], v[116:119]
	v_mfma_f32_16x16x32_bf16 v[112:115], v[196:199], v[204:207], v[112:115]
	v_mfma_f32_16x16x32_bf16 v[100:103], v[172:175], v[212:215], v[100:103]
	v_mfma_f32_16x16x32_bf16 v[96:99], v[196:199], v[212:215], v[96:99]
	v_mfma_f32_16x16x32_bf16 v[84:87], v[172:175], v[220:223], v[84:87]
	v_mfma_f32_16x16x32_bf16 v[80:83], v[196:199], v[220:223], v[80:83]
	v_mfma_f32_16x16x32_bf16 v[68:71], v[172:175], v[228:231], v[68:71]
	v_mfma_f32_16x16x32_bf16 v[64:67], v[196:199], v[228:231], v[64:67]
	s_barrier
; #define PG8_STAGE(bufoff, gbase, voff) do { _Pragma("unroll") for (int _i = 0; _i < 2; ++_i) \
;         __builtin_amdgcn_global_load_lds((const unsigned*)((const char*)(gbase) + (voff)[_i]), (PG8_LAS unsigned*)(lds + (bufoff) + ldsw + _i * 8192), 16, 0, 0); } while (0)
; #define PG8_LDA(dst, b, h) do { _Pragma("unroll") for (int m = 0; m < 4; ++m) _Pragma("unroll") for (int k = 0; k < 2; ++k) dst[m][k] = *(const PG8_LAS bf16x8*)(lds + PG8_SA(b, h) + aoff + m * 2048 + k * 1024); } while (0)
; #define PG8_MMA(ai, bj, At, Bt) do { __builtin_amdgcn_s_setprio(1); _Pragma("unroll") for (int m = 0; m < 4; ++m) _Pragma("unroll") for (int n = 0; n < 2; ++n) _Pragma("unroll") for (int k = 0; k < 2; ++k) \
;         acc[ai][bj][m][n] = __builtin_amdgcn_mfma_f32_16x16x32_bf16(Bt[n][k], At[m][k], acc[ai][bj][m][n], 0, 0, 0); __builtin_amdgcn_s_setprio(0); } while (0)
; #define PG8_WAIT_V(n) asm volatile("s_waitcnt vmcnt(" #n ")" ::: "memory")
; #define PG8_WAIT_L(n) asm volatile("s_waitcnt lgkmcnt(" #n ")" ::: "memory")
; #define PG8_BAR __builtin_amdgcn_s_barrier()
; #define PG8_SCHED __builtin_amdgcn_sched_barrier(0)
; template <class Epi, class Sched, bool ALIGN_EPI = false, bool SP2 = false>
; __device__ __forceinline__ void gemm_phase(PG8_LAS unsigned char* lds, const Gemm g, const Sched& S, const Epi& E) {
;     ...
;             PG8_LDA(At, 1, 1); PG8_STAGE(PG8_SB(1, 0), b3, voffB); PG8_STAGE(PG8_SB(1, 1), b3 + hstep, voffB); PG8_STAGE(PG8_SA(1, 0), a3, voffA);
;             PG8_WAIT_V(8); PG8_WAIT_L(0); PG8_BAR; PG8_MMA(1, 0, At, B0); PG8_MMA(1, 1, At, B1); PG8_BAR; PG8_SCHED;
	s_setprio 0
	s_add_i32 s68, s93, s0
	v_lshl_add_u64 v[150:151], v[150:151], 0, s[18:19]
	s_mov_b32 m0, s68
	ds_read_b128 v[200:203], v149 offset:49152
	ds_read_b128 v[204:207], v149 offset:50176
	ds_read_b128 v[208:211], v149 offset:51200
	ds_read_b128 v[212:215], v149 offset:52224
	ds_read_b128 v[216:219], v149 offset:53248
	ds_read_b128 v[220:223], v149 offset:54272
	ds_read_b128 v[224:227], v149 offset:55296
	ds_read_b128 v[228:231], v149 offset:56320
	global_load_lds_dwordx4 v[150:151], off
	s_add_i32 m0, s68, 0x2000
	s_add_u32 s68, s78, 0x80080
	v_lshl_add_u64 v[150:151], v[182:183], 0, s[18:19]
	s_addc_u32 s69, s79, 0
	s_add_i32 s78, s82, s0
	global_load_lds_dwordx4 v[150:151], off
	v_lshl_add_u64 v[150:151], s[68:69], 0, v[152:153]
	s_mov_b32 m0, s78
	s_nop 0
	global_load_lds_dwordx4 v[150:151], off
	v_lshl_add_u64 v[150:151], s[68:69], 0, v[128:129]
	s_add_i32 m0, s78, 0x2000
	s_nop 0
	global_load_lds_dwordx4 v[150:151], off
	v_lshl_add_u64 v[150:151], v[184:185], 0, s[18:19]
	s_mov_b32 m0, s22
	s_nop 0
	global_load_lds_dwordx4 v[150:151], off
	v_lshl_add_u64 v[150:151], v[188:189], 0, s[18:19]
	s_mov_b32 m0, s23
	s_nop 0
	global_load_lds_dwordx4 v[150:151], off
	s_waitcnt vmcnt(8)
	s_waitcnt lgkmcnt(0)
	s_setprio 1
	s_barrier
	v_mfma_f32_16x16x32_bf16 v[60:63], v[140:143], v[200:203], v[60:63]
	v_mfma_f32_16x16x32_bf16 v[56:59], v[160:163], v[200:203], v[56:59]
	v_mfma_f32_16x16x32_bf16 v[44:47], v[140:143], v[208:211], v[44:47]
	v_mfma_f32_16x16x32_bf16 v[40:43], v[160:163], v[208:211], v[40:43]
	v_mfma_f32_16x16x32_bf16 v[28:31], v[140:143], v[216:219], v[28:31]
	v_mfma_f32_16x16x32_bf16 v[24:27], v[160:163], v[216:219], v[24:27]
	v_mfma_f32_16x16x32_bf16 v[12:15], v[140:143], v[224:227], v[12:15]
	v_mfma_f32_16x16x32_bf16 v[8:11], v[160:163], v[224:227], v[8:11]
	v_mfma_f32_16x16x32_bf16 v[60:63], v[156:159], v[204:207], v[60:63]
	v_mfma_f32_16x16x32_bf16 v[56:59], v[164:167], v[204:207], v[56:59]
	v_mfma_f32_16x16x32_bf16 v[44:47], v[156:159], v[212:215], v[44:47]
	v_mfma_f32_16x16x32_bf16 v[40:43], v[164:167], v[212:215], v[40:43]
	v_mfma_f32_16x16x32_bf16 v[28:31], v[156:159], v[220:223], v[28:31]
	v_mfma_f32_16x16x32_bf16 v[24:27], v[164:167], v[220:223], v[24:27]
	v_mfma_f32_16x16x32_bf16 v[12:15], v[156:159], v[228:231], v[12:15]
	v_mfma_f32_16x16x32_bf16 v[8:11], v[164:167], v[228:231], v[8:11]
	v_mfma_f32_16x16x32_bf16 v[52:55], v[168:171], v[200:203], v[52:55]
	v_mfma_f32_16x16x32_bf16 v[48:51], v[192:195], v[200:203], v[48:51]
	v_mfma_f32_16x16x32_bf16 v[36:39], v[168:171], v[208:211], v[36:39]
	v_mfma_f32_16x16x32_bf16 v[32:35], v[192:195], v[208:211], v[32:35]
	v_mfma_f32_16x16x32_bf16 v[20:23], v[168:171], v[216:219], v[20:23]
	v_mfma_f32_16x16x32_bf16 v[16:19], v[192:195], v[216:219], v[16:19]
	v_mfma_f32_16x16x32_bf16 v[4:7], v[168:171], v[224:227], v[4:7]
	v_mfma_f32_16x16x32_bf16 v[0:3], v[192:195], v[224:227], v[0:3]
	v_mfma_f32_16x16x32_bf16 v[52:55], v[172:175], v[204:207], v[52:55]
	v_mfma_f32_16x16x32_bf16 v[48:51], v[196:199], v[204:207], v[48:51]
	v_mfma_f32_16x16x32_bf16 v[36:39], v[172:175], v[212:215], v[36:39]
	v_mfma_f32_16x16x32_bf16 v[32:35], v[196:199], v[212:215], v[32:35]
	v_mfma_f32_16x16x32_bf16 v[20:23], v[172:175], v[220:223], v[20:23]
	v_mfma_f32_16x16x32_bf16 v[16:19], v[196:199], v[220:223], v[16:19]
	v_mfma_f32_16x16x32_bf16 v[4:7], v[172:175], v[228:231], v[4:7]
	v_mfma_f32_16x16x32_bf16 v[0:3], v[196:199], v[228:231], v[0:3]
	s_barrier
	s_setprio 0
	s_add_i32 s71, s71, 2
	s_add_u32 s42, s42, 0x100
	s_addc_u32 s43, s43, 0
	s_add_u32 s59, s59, 0x100
	s_addc_u32 s63, s63, 0
	s_cmp_gt_u32 s71, 29
	s_cbranch_scc1 .Lpeel_exit_165

; #define PG8_STAGE(bufoff, gbase, voff) do { _Pragma("unroll") for (int _i = 0; _i < 2; ++_i) \
;         __builtin_amdgcn_global_load_lds((const unsigned*)((const char*)(gbase) + (voff)[_i]), (PG8_LAS unsigned*)(lds + (bufoff) + ldsw + _i * 8192), 16, 0, 0); } while (0)
; #define PG8_LDA(dst, b, h) do { _Pragma("unroll") for (int m = 0; m < 4; ++m) _Pragma("unroll") for (int k = 0; k < 2; ++k) dst[m][k] = *(const PG8_LAS bf16x8*)(lds + PG8_SA(b, h) + aoff + m * 2048 + k * 1024); } while (0)
; #define PG8_LDB(dst, b, h) do { _Pragma("unroll") for (int n = 0; n < 2; ++n) _Pragma("unroll") for (int k = 0; k < 2; ++k) dst[n][k] = *(const PG8_LAS bf16x8*)(lds + PG8_SB(b, h) + boff + n * 2048 + k * 1024); } while (0)
; #define PG8_MMA(ai, bj, At, Bt) do { __builtin_amdgcn_s_setprio(1); _Pragma("unroll") for (int m = 0; m < 4; ++m) _Pragma("unroll") for (int n = 0; n < 2; ++n) _Pragma("unroll") for (int k = 0; k < 2; ++k) \
;         acc[ai][bj][m][n] = __builtin_amdgcn_mfma_f32_16x16x32_bf16(Bt[n][k], At[m][k], acc[ai][bj][m][n], 0, 0, 0); __builtin_amdgcn_s_setprio(0); } while (0)
; #define PG8_WAIT_V(n) asm volatile("s_waitcnt vmcnt(" #n ")" ::: "memory")
; #define PG8_WAIT_L(n) asm volatile("s_waitcnt lgkmcnt(" #n ")" ::: "memory")
; template <class Epi, class Sched, bool ALIGN_EPI = false, bool SP2 = false>
; __device__ __forceinline__ void gemm_phase(PG8_LAS unsigned char* lds, const Gemm g, const Sched& S, const Epi& E) {
;     ...
;             const bool last = (t == nt - 2);
;             const char* a1 = cA + (size_t)(t + 1) * kstep;
;             const char* a2 = last ? nA : cA + (size_t)(t + 2) * kstep; const char* b2 = last ? nB : cB + (size_t)(t + 2) * kstep;
;             const char* a3 = a2 + kstep; const char* b3 = b2 + kstep;
;             if (last && has_next) S.a_ready(nxt);
;             if constexpr (SP2) {
;             PG8_LDB(B0, 0, 0); PG8_LDB(B1, 0, 1); PG8_SCHED; PG8_LDA(At, 0, 0); PG8_STAGE(PG8_SA(1, 1), a1 + hstep, voffA);
;             PG8_WAIT_V(8); PG8_WAIT_L(0); PG8_BAR; PG8_MMA(0, 0, At, B0); PG8_MMA(0, 1, At, B1); PG8_BAR; PG8_SCHED;
;             PG8_LDA(At, 0, 1); PG8_STAGE(PG8_SB(0, 0), b2, voffB); PG8_STAGE(PG8_SB(0, 1), b2 + hstep, voffB); PG8_STAGE(PG8_SA(0, 0), a2, voffA);
;             PG8_WAIT_V(8); PG8_WAIT_L(0); PG8_BAR; PG8_MMA(1, 0, At, B0); PG8_MMA(1, 1, At, B1); PG8_BAR; PG8_SCHED;
.LBB0_217:
	s_add_u32 s44, s86, 0x80
	s_addc_u32 s45, s87, 0
	s_add_u32 s86, s46, 0x100
	v_mov_b32_e32 v0, 0
	s_addc_u32 s87, s47, 0
	s_mov_b32 s46, 0
	s_add_i32 vcc_lo, s46, 2
	s_add_u32 s68, s44, 0x80
	s_addc_u32 s47, s45, 0
	s_add_i32 vcc_hi, 0, 0x10000
	s_cmp_eq_u32 s15, s46
	s_cselect_b32 s47, s83, s47
	s_cselect_b32 s46, s82, s68
	v_add_u32_e32 v146, vcc_hi, v149
	s_cselect_b32 s69, s85, s87
	s_cselect_b32 s68, s84, s86
	s_add_i32 s96, 0, 0x14000
	ds_read_b128 v[138:141], v146
	ds_read_b128 v[142:145], v146 offset:1024
	ds_read_b128 v[156:159], v146 offset:2048
	ds_read_b128 v[160:163], v146 offset:3072
	v_add_u32_e32 v146, s96, v149
	ds_read_b128 v[164:167], v146
	ds_read_b128 v[168:171], v146 offset:1024
	ds_read_b128 v[172:175], v146 offset:2048
	ds_read_b128 v[192:195], v146 offset:3072
	v_lshl_add_u64 v[146:147], s[44:45], 0, v[134:135]
	s_add_i32 m0, s54, 0xc000
	ds_read_b128 v[196:199], v151
	ds_read_b128 v[200:203], v151 offset:1024
	ds_read_b128 v[204:207], v151 offset:2048
	ds_read_b128 v[208:211], v151 offset:3072
	ds_read_b128 v[212:215], v151 offset:4096
	ds_read_b128 v[216:219], v151 offset:5120
	ds_read_b128 v[220:223], v151 offset:6144
	ds_read_b128 v[224:227], v151 offset:7168
	global_load_lds_dwordx4 v[146:147], off
	v_lshl_add_u64 v[146:147], s[44:45], 0, v[136:137]
	s_add_i32 m0, s54, 0xe000
	s_nop 0
	global_load_lds_dwordx4 v[146:147], off
	s_waitcnt vmcnt(8)
	s_waitcnt lgkmcnt(0)
	s_setprio 1
	s_barrier
	v_mfma_f32_16x16x32_bf16 v[124:127], v[138:141], v[196:199], 0
	v_mfma_f32_16x16x32_bf16 v[120:123], v[156:159], v[196:199], 0
	v_mfma_f32_16x16x32_bf16 v[108:111], v[138:141], v[204:207], 0
	v_mfma_f32_16x16x32_bf16 v[104:107], v[156:159], v[204:207], 0
	v_mfma_f32_16x16x32_bf16 v[92:95], v[138:141], v[212:215], 0
	v_mfma_f32_16x16x32_bf16 v[88:91], v[156:159], v[212:215], 0
	v_mfma_f32_16x16x32_bf16 v[76:79], v[138:141], v[220:223], 0
	v_mfma_f32_16x16x32_bf16 v[72:75], v[156:159], v[220:223], 0
	v_mfma_f32_16x16x32_bf16 v[124:127], v[142:145], v[200:203], v[124:127]
	v_mfma_f32_16x16x32_bf16 v[120:123], v[160:163], v[200:203], v[120:123]
	v_mfma_f32_16x16x32_bf16 v[108:111], v[142:145], v[208:211], v[108:111]
	v_mfma_f32_16x16x32_bf16 v[104:107], v[160:163], v[208:211], v[104:107]
	v_mfma_f32_16x16x32_bf16 v[92:95], v[142:145], v[216:219], v[92:95]
	v_mfma_f32_16x16x32_bf16 v[88:91], v[160:163], v[216:219], v[88:91]
	v_mfma_f32_16x16x32_bf16 v[76:79], v[142:145], v[224:227], v[76:79]
	v_mfma_f32_16x16x32_bf16 v[72:75], v[160:163], v[224:227], v[72:75]
	v_mfma_f32_16x16x32_bf16 v[116:119], v[164:167], v[196:199], 0
	v_mfma_f32_16x16x32_bf16 v[112:115], v[172:175], v[196:199], 0
	v_mfma_f32_16x16x32_bf16 v[100:103], v[164:167], v[204:207], 0
	v_mfma_f32_16x16x32_bf16 v[96:99], v[172:175], v[204:207], 0
	v_mfma_f32_16x16x32_bf16 v[84:87], v[164:167], v[212:215], 0
	v_mfma_f32_16x16x32_bf16 v[80:83], v[172:175], v[212:215], 0
	v_mfma_f32_16x16x32_bf16 v[68:71], v[164:167], v[220:223], 0
	v_mfma_f32_16x16x32_bf16 v[64:67], v[172:175], v[220:223], 0
	v_mfma_f32_16x16x32_bf16 v[116:119], v[168:171], v[200:203], v[116:119]
	v_mfma_f32_16x16x32_bf16 v[112:115], v[192:195], v[200:203], v[112:115]
	v_mfma_f32_16x16x32_bf16 v[100:103], v[168:171], v[208:211], v[100:103]
	v_mfma_f32_16x16x32_bf16 v[96:99], v[192:195], v[208:211], v[96:99]
	v_mfma_f32_16x16x32_bf16 v[84:87], v[168:171], v[216:219], v[84:87]
	v_mfma_f32_16x16x32_bf16 v[80:83], v[192:195], v[216:219], v[80:83]
	v_mfma_f32_16x16x32_bf16 v[68:71], v[168:171], v[224:227], v[68:71]
	v_mfma_f32_16x16x32_bf16 v[64:67], v[192:195], v[224:227], v[64:67]
	s_barrier
	s_setprio 0
	s_add_i32 vcc_hi, vcc_hi, s63
	v_lshl_add_u64 v[146:147], s[68:69], 0, v[152:153]
	s_mov_b32 m0, vcc_hi
	ds_read_b128 v[196:199], v151 offset:16384
	ds_read_b128 v[200:203], v151 offset:17408
	ds_read_b128 v[204:207], v151 offset:18432
	ds_read_b128 v[208:211], v151 offset:19456
	ds_read_b128 v[212:215], v151 offset:20480
	ds_read_b128 v[216:219], v151 offset:21504
	ds_read_b128 v[220:223], v151 offset:22528
	ds_read_b128 v[224:227], v151 offset:23552
	global_load_lds_dwordx4 v[146:147], off
	s_add_i32 m0, vcc_hi, 0x2000
	v_lshl_add_u64 v[182:183], s[68:69], 0, v[128:129]
	s_add_u32 s68, s68, s48
	s_addc_u32 s69, s69, 0
	s_add_i32 s96, s96, s63
	global_load_lds_dwordx4 v[182:183], off
	v_lshl_add_u64 v[184:185], s[68:69], 0, v[152:153]
	s_mov_b32 m0, s96
	v_lshl_add_u64 v[188:189], s[68:69], 0, v[128:129]
	global_load_lds_dwordx4 v[184:185], off
	s_add_i32 m0, s96, 0x2000
	v_lshl_add_u64 v[190:191], s[46:47], 0, v[132:133]
	global_load_lds_dwordx4 v[188:189], off
	s_mov_b32 m0, s54
	v_lshl_add_u64 v[228:229], s[46:47], 0, v[130:131]
	global_load_lds_dwordx4 v[190:191], off
	s_mov_b32 m0, s55
	s_nop 0
	global_load_lds_dwordx4 v[228:229], off
	s_waitcnt vmcnt(8)
	s_waitcnt lgkmcnt(0)
	s_setprio 1
	s_barrier
; #define PG8_STAGE(bufoff, gbase, voff) do { _Pragma("unroll") for (int _i = 0; _i < 2; ++_i) \
;         __builtin_amdgcn_global_load_lds((const unsigned*)((const char*)(gbase) + (voff)[_i]), (PG8_LAS unsigned*)(lds + (bufoff) + ldsw + _i * 8192), 16, 0, 0); } while (0)
; #define PG8_LDA(dst, b, h) do { _Pragma("unroll") for (int m = 0; m < 4; ++m) _Pragma("unroll") for (int k = 0; k < 2; ++k) dst[m][k] = *(const PG8_LAS bf16x8*)(lds + PG8_SA(b, h) + aoff + m * 2048 + k * 1024); } while (0)
; #define PG8_LDB(dst, b, h) do { _Pragma("unroll") for (int n = 0; n < 2; ++n) _Pragma("unroll") for (int k = 0; k < 2; ++k) dst[n][k] = *(const PG8_LAS bf16x8*)(lds + PG8_SB(b, h) + boff + n * 2048 + k * 1024); } while (0)
; #define PG8_MMA(ai, bj, At, Bt) do { __builtin_amdgcn_s_setprio(1); _Pragma("unroll") for (int m = 0; m < 4; ++m) _Pragma("unroll") for (int n = 0; n < 2; ++n) _Pragma("unroll") for (int k = 0; k < 2; ++k) \
;         acc[ai][bj][m][n] = __builtin_amdgcn_mfma_f32_16x16x32_bf16(Bt[n][k], At[m][k], acc[ai][bj][m][n], 0, 0, 0); __builtin_amdgcn_s_setprio(0); } while (0)
; #define PG8_WAIT_V(n) asm volatile("s_waitcnt vmcnt(" #n ")" ::: "memory")
; #define PG8_WAIT_L(n) asm volatile("s_waitcnt lgkmcnt(" #n ")" ::: "memory")
; #define PG8_BAR __builtin_amdgcn_s_barrier()
; #define PG8_SCHED __builtin_amdgcn_sched_barrier(0)
; template <class Epi, class Sched, bool ALIGN_EPI = false, bool SP2 = false>
; __device__ __forceinline__ void gemm_phase(PG8_LAS unsigned char* lds, const Gemm g, const Sched& S, const Epi& E) {
;     ...
;             PG8_WAIT_V(8); PG8_WAIT_L(0); PG8_BAR; PG8_MMA(1, 0, At, B0); PG8_MMA(1, 1, At, B1); PG8_BAR; PG8_SCHED;
;             PG8_LDB(B0, 1, 0); PG8_LDB(B1, 1, 1); PG8_SCHED; PG8_LDA(At, 1, 0); PG8_STAGE(PG8_SA(0, 1), a2 + hstep, voffA);
;             PG8_WAIT_V(8); PG8_WAIT_L(0); PG8_BAR; PG8_MMA(0, 0, At, B0); PG8_MMA(0, 1, At, B1); PG8_BAR; PG8_SCHED;
;             PG8_LDA(At, 1, 1); PG8_STAGE(PG8_SB(1, 0), b3, voffB); PG8_STAGE(PG8_SB(1, 1), b3 + hstep, voffB); PG8_STAGE(PG8_SA(1, 0), a3, voffA);
	v_mfma_f32_16x16x32_bf16 v[60:63], v[138:141], v[196:199], 0
	v_mfma_f32_16x16x32_bf16 v[56:59], v[156:159], v[196:199], 0
	v_mfma_f32_16x16x32_bf16 v[44:47], v[138:141], v[204:207], 0
	v_mfma_f32_16x16x32_bf16 v[40:43], v[156:159], v[204:207], 0
	v_mfma_f32_16x16x32_bf16 v[28:31], v[138:141], v[212:215], 0
	v_mfma_f32_16x16x32_bf16 v[24:27], v[156:159], v[212:215], 0
	v_mfma_f32_16x16x32_bf16 v[12:15], v[138:141], v[220:223], 0
	v_mfma_f32_16x16x32_bf16 v[8:11], v[156:159], v[220:223], 0
	v_mfma_f32_16x16x32_bf16 v[60:63], v[142:145], v[200:203], v[60:63]
	v_mfma_f32_16x16x32_bf16 v[56:59], v[160:163], v[200:203], v[56:59]
	v_mfma_f32_16x16x32_bf16 v[44:47], v[142:145], v[208:211], v[44:47]
	v_mfma_f32_16x16x32_bf16 v[40:43], v[160:163], v[208:211], v[40:43]
	v_mfma_f32_16x16x32_bf16 v[28:31], v[142:145], v[216:219], v[28:31]
	v_mfma_f32_16x16x32_bf16 v[24:27], v[160:163], v[216:219], v[24:27]
	v_mfma_f32_16x16x32_bf16 v[12:15], v[142:145], v[224:227], v[12:15]
	v_mfma_f32_16x16x32_bf16 v[8:11], v[160:163], v[224:227], v[8:11]
	v_mfma_f32_16x16x32_bf16 v[52:55], v[164:167], v[196:199], 0
	v_mfma_f32_16x16x32_bf16 v[48:51], v[172:175], v[196:199], 0
	v_mfma_f32_16x16x32_bf16 v[36:39], v[164:167], v[204:207], 0
	v_mfma_f32_16x16x32_bf16 v[32:35], v[172:175], v[204:207], 0
	v_mfma_f32_16x16x32_bf16 v[20:23], v[164:167], v[212:215], 0
	v_mfma_f32_16x16x32_bf16 v[16:19], v[172:175], v[212:215], 0
	v_mfma_f32_16x16x32_bf16 v[4:7], v[164:167], v[220:223], 0
	v_mfma_f32_16x16x32_bf16 v[0:3], v[172:175], v[220:223], 0
	v_mfma_f32_16x16x32_bf16 v[52:55], v[168:171], v[200:203], v[52:55]
	v_mfma_f32_16x16x32_bf16 v[48:51], v[192:195], v[200:203], v[48:51]
	v_mfma_f32_16x16x32_bf16 v[36:39], v[168:171], v[208:211], v[36:39]
	v_mfma_f32_16x16x32_bf16 v[32:35], v[192:195], v[208:211], v[32:35]
	v_mfma_f32_16x16x32_bf16 v[20:23], v[168:171], v[216:219], v[20:23]
	v_mfma_f32_16x16x32_bf16 v[16:19], v[192:195], v[216:219], v[16:19]
	v_mfma_f32_16x16x32_bf16 v[4:7], v[168:171], v[224:227], v[4:7]
	v_mfma_f32_16x16x32_bf16 v[0:3], v[192:195], v[224:227], v[0:3]
	s_barrier
	s_setprio 0
	v_add_u32_e32 v155, s93, v149
	s_add_i32 s68, 0, 0x1c000
	ds_read_b128 v[138:141], v155
	ds_read_b128 v[142:145], v155 offset:1024
	ds_read_b128 v[156:159], v155 offset:2048
	ds_read_b128 v[160:163], v155 offset:3072
	v_add_u32_e32 v155, s68, v149
	ds_read_b128 v[164:167], v155
	ds_read_b128 v[168:171], v155 offset:1024
	ds_read_b128 v[172:175], v155 offset:2048
	ds_read_b128 v[192:195], v155 offset:3072
	s_add_u32 s46, s46, s48
	s_addc_u32 s47, s47, 0
	s_mov_b32 m0, s34
	v_lshl_add_u64 v[230:231], s[46:47], 0, v[132:133]
	ds_read_b128 v[196:199], v151 offset:32768
	ds_read_b128 v[200:203], v151 offset:33792
	ds_read_b128 v[204:207], v151 offset:34816
	ds_read_b128 v[208:211], v151 offset:35840
	ds_read_b128 v[212:215], v151 offset:36864
	ds_read_b128 v[216:219], v151 offset:37888
	ds_read_b128 v[220:223], v151 offset:38912
	ds_read_b128 v[224:227], v151 offset:39936
	global_load_lds_dwordx4 v[230:231], off
	v_lshl_add_u64 v[230:231], s[46:47], 0, v[130:131]
	s_mov_b32 m0, s95
	s_nop 0
	global_load_lds_dwordx4 v[230:231], off
	s_waitcnt vmcnt(8)
	s_waitcnt lgkmcnt(0)
	s_setprio 1
	s_barrier
	v_mfma_f32_16x16x32_bf16 v[124:127], v[138:141], v[196:199], v[124:127]
	v_mfma_f32_16x16x32_bf16 v[120:123], v[156:159], v[196:199], v[120:123]
	v_mfma_f32_16x16x32_bf16 v[108:111], v[138:141], v[204:207], v[108:111]
	v_mfma_f32_16x16x32_bf16 v[104:107], v[156:159], v[204:207], v[104:107]
	v_mfma_f32_16x16x32_bf16 v[92:95], v[138:141], v[212:215], v[92:95]
	v_mfma_f32_16x16x32_bf16 v[88:91], v[156:159], v[212:215], v[88:91]
	v_mfma_f32_16x16x32_bf16 v[76:79], v[138:141], v[220:223], v[76:79]
	v_mfma_f32_16x16x32_bf16 v[72:75], v[156:159], v[220:223], v[72:75]
	v_mfma_f32_16x16x32_bf16 v[124:127], v[142:145], v[200:203], v[124:127]
	v_mfma_f32_16x16x32_bf16 v[120:123], v[160:163], v[200:203], v[120:123]
	v_mfma_f32_16x16x32_bf16 v[108:111], v[142:145], v[208:211], v[108:111]
	v_mfma_f32_16x16x32_bf16 v[104:107], v[160:163], v[208:211], v[104:107]
	v_mfma_f32_16x16x32_bf16 v[92:95], v[142:145], v[216:219], v[92:95]
	v_mfma_f32_16x16x32_bf16 v[88:91], v[160:163], v[216:219], v[88:91]
	v_mfma_f32_16x16x32_bf16 v[76:79], v[142:145], v[224:227], v[76:79]
	v_mfma_f32_16x16x32_bf16 v[72:75], v[160:163], v[224:227], v[72:75]
	v_mfma_f32_16x16x32_bf16 v[116:119], v[164:167], v[196:199], v[116:119]
	v_mfma_f32_16x16x32_bf16 v[112:115], v[172:175], v[196:199], v[112:115]
	v_mfma_f32_16x16x32_bf16 v[100:103], v[164:167], v[204:207], v[100:103]
	v_mfma_f32_16x16x32_bf16 v[96:99], v[172:175], v[204:207], v[96:99]
	v_mfma_f32_16x16x32_bf16 v[84:87], v[164:167], v[212:215], v[84:87]
	v_mfma_f32_16x16x32_bf16 v[80:83], v[172:175], v[212:215], v[80:83]
	v_mfma_f32_16x16x32_bf16 v[68:71], v[164:167], v[220:223], v[68:71]
	v_mfma_f32_16x16x32_bf16 v[64:67], v[172:175], v[220:223], v[64:67]
	v_mfma_f32_16x16x32_bf16 v[116:119], v[168:171], v[200:203], v[116:119]
	v_mfma_f32_16x16x32_bf16 v[112:115], v[192:195], v[200:203], v[112:115]
	v_mfma_f32_16x16x32_bf16 v[100:103], v[168:171], v[208:211], v[100:103]
	v_mfma_f32_16x16x32_bf16 v[96:99], v[192:195], v[208:211], v[96:99]
	v_mfma_f32_16x16x32_bf16 v[84:87], v[168:171], v[216:219], v[84:87]
	v_mfma_f32_16x16x32_bf16 v[80:83], v[192:195], v[216:219], v[80:83]
	v_mfma_f32_16x16x32_bf16 v[68:71], v[168:171], v[224:227], v[68:71]
	v_mfma_f32_16x16x32_bf16 v[64:67], v[192:195], v[224:227], v[64:67]
	s_barrier
; #define PG8_STAGE(bufoff, gbase, voff) do { _Pragma("unroll") for (int _i = 0; _i < 2; ++_i) \
;         __builtin_amdgcn_global_load_lds((const unsigned*)((const char*)(gbase) + (voff)[_i]), (PG8_LAS unsigned*)(lds + (bufoff) + ldsw + _i * 8192), 16, 0, 0); } while (0)
; #define PG8_LDA(dst, b, h) do { _Pragma("unroll") for (int m = 0; m < 4; ++m) _Pragma("unroll") for (int k = 0; k < 2; ++k) dst[m][k] = *(const PG8_LAS bf16x8*)(lds + PG8_SA(b, h) + aoff + m * 2048 + k * 1024); } while (0)
; #define PG8_MMA(ai, bj, At, Bt) do { __builtin_amdgcn_s_setprio(1); _Pragma("unroll") for (int m = 0; m < 4; ++m) _Pragma("unroll") for (int n = 0; n < 2; ++n) _Pragma("unroll") for (int k = 0; k < 2; ++k) \
;         acc[ai][bj][m][n] = __builtin_amdgcn_mfma_f32_16x16x32_bf16(Bt[n][k], At[m][k], acc[ai][bj][m][n], 0, 0, 0); __builtin_amdgcn_s_setprio(0); } while (0)
; #define PG8_WAIT_V(n) asm volatile("s_waitcnt vmcnt(" #n ")" ::: "memory")
; #define PG8_WAIT_L(n) asm volatile("s_waitcnt lgkmcnt(" #n ")" ::: "memory")
; #define PG8_BAR __builtin_amdgcn_s_barrier()
; #define PG8_SCHED __builtin_amdgcn_sched_barrier(0)
; template <class Epi, class Sched, bool ALIGN_EPI = false, bool SP2 = false>
; __device__ __forceinline__ void gemm_phase(PG8_LAS unsigned char* lds, const Gemm g, const Sched& S, const Epi& E) {
;     ...
;             PG8_LDA(At, 1, 1); PG8_STAGE(PG8_SB(1, 0), b3, voffB); PG8_STAGE(PG8_SB(1, 1), b3 + hstep, voffB); PG8_STAGE(PG8_SA(1, 0), a3, voffA);
;             PG8_WAIT_V(8); PG8_WAIT_L(0); PG8_BAR; PG8_MMA(1, 0, At, B0); PG8_MMA(1, 1, At, B1); PG8_BAR; PG8_SCHED;
	s_setprio 0
	s_add_i32 s46, s93, s63
	v_lshl_add_u64 v[146:147], v[146:147], 0, s[18:19]
	s_mov_b32 m0, s46
	ds_read_b128 v[196:199], v151 offset:49152
	ds_read_b128 v[200:203], v151 offset:50176
	ds_read_b128 v[204:207], v151 offset:51200
	ds_read_b128 v[208:211], v151 offset:52224
	ds_read_b128 v[212:215], v151 offset:53248
	ds_read_b128 v[216:219], v151 offset:54272
	ds_read_b128 v[220:223], v151 offset:55296
	ds_read_b128 v[224:227], v151 offset:56320
	global_load_lds_dwordx4 v[146:147], off
	v_lshl_add_u64 v[146:147], v[182:183], 0, s[18:19]
	s_add_i32 m0, s46, 0x2000
	s_add_i32 s46, s68, s63
	global_load_lds_dwordx4 v[146:147], off
	v_lshl_add_u64 v[146:147], v[184:185], 0, s[18:19]
	s_mov_b32 m0, s46
	s_nop 0
	global_load_lds_dwordx4 v[146:147], off
	v_lshl_add_u64 v[146:147], v[188:189], 0, s[18:19]
	s_add_i32 m0, s46, 0x2000
	s_nop 0
	global_load_lds_dwordx4 v[146:147], off
	v_lshl_add_u64 v[146:147], v[190:191], 0, s[18:19]
	s_mov_b32 m0, s0
	s_nop 0
	global_load_lds_dwordx4 v[146:147], off
	v_lshl_add_u64 v[146:147], v[228:229], 0, s[18:19]
	s_mov_b32 m0, s58
	s_nop 0
	global_load_lds_dwordx4 v[146:147], off
	s_waitcnt vmcnt(8)
	s_waitcnt lgkmcnt(0)
	s_setprio 1
	s_barrier
	v_mfma_f32_16x16x32_bf16 v[60:63], v[138:141], v[196:199], v[60:63]
	v_mfma_f32_16x16x32_bf16 v[56:59], v[156:159], v[196:199], v[56:59]
	v_mfma_f32_16x16x32_bf16 v[44:47], v[138:141], v[204:207], v[44:47]
	v_mfma_f32_16x16x32_bf16 v[40:43], v[156:159], v[204:207], v[40:43]
	v_mfma_f32_16x16x32_bf16 v[28:31], v[138:141], v[212:215], v[28:31]
	v_mfma_f32_16x16x32_bf16 v[24:27], v[156:159], v[212:215], v[24:27]
	v_mfma_f32_16x16x32_bf16 v[12:15], v[138:141], v[220:223], v[12:15]
	v_mfma_f32_16x16x32_bf16 v[8:11], v[156:159], v[220:223], v[8:11]
	v_mfma_f32_16x16x32_bf16 v[60:63], v[142:145], v[200:203], v[60:63]
	v_mfma_f32_16x16x32_bf16 v[56:59], v[160:163], v[200:203], v[56:59]
	v_mfma_f32_16x16x32_bf16 v[44:47], v[142:145], v[208:211], v[44:47]
	v_mfma_f32_16x16x32_bf16 v[40:43], v[160:163], v[208:211], v[40:43]
	v_mfma_f32_16x16x32_bf16 v[28:31], v[142:145], v[216:219], v[28:31]
	v_mfma_f32_16x16x32_bf16 v[24:27], v[160:163], v[216:219], v[24:27]
	v_mfma_f32_16x16x32_bf16 v[12:15], v[142:145], v[224:227], v[12:15]
	v_mfma_f32_16x16x32_bf16 v[8:11], v[160:163], v[224:227], v[8:11]
	v_mfma_f32_16x16x32_bf16 v[52:55], v[164:167], v[196:199], v[52:55]
	v_mfma_f32_16x16x32_bf16 v[48:51], v[172:175], v[196:199], v[48:51]
	v_mfma_f32_16x16x32_bf16 v[36:39], v[164:167], v[204:207], v[36:39]
	v_mfma_f32_16x16x32_bf16 v[32:35], v[172:175], v[204:207], v[32:35]
	v_mfma_f32_16x16x32_bf16 v[20:23], v[164:167], v[212:215], v[20:23]
	v_mfma_f32_16x16x32_bf16 v[16:19], v[172:175], v[212:215], v[16:19]
	v_mfma_f32_16x16x32_bf16 v[4:7], v[164:167], v[220:223], v[4:7]
	v_mfma_f32_16x16x32_bf16 v[0:3], v[172:175], v[220:223], v[0:3]
	v_mfma_f32_16x16x32_bf16 v[52:55], v[168:171], v[200:203], v[52:55]
	v_mfma_f32_16x16x32_bf16 v[48:51], v[192:195], v[200:203], v[48:51]
	v_mfma_f32_16x16x32_bf16 v[36:39], v[168:171], v[208:211], v[36:39]
	v_mfma_f32_16x16x32_bf16 v[32:35], v[192:195], v[208:211], v[32:35]
	v_mfma_f32_16x16x32_bf16 v[20:23], v[168:171], v[216:219], v[20:23]
	v_mfma_f32_16x16x32_bf16 v[16:19], v[192:195], v[216:219], v[16:19]
	v_mfma_f32_16x16x32_bf16 v[4:7], v[168:171], v[224:227], v[4:7]
	v_mfma_f32_16x16x32_bf16 v[0:3], v[192:195], v[224:227], v[0:3]
	s_barrier
	s_setprio 0
	s_add_u32 s44, s44, 0x100
	s_addc_u32 s45, s45, 0
	s_add_u32 s86, s86, 0x100
	s_addc_u32 s87, s87, 0
	s_cmp_ge_u32 vcc_lo, s14
	s_mov_b32 s46, vcc_lo
	s_cbranch_scc1 .Lpeel_exit_218

; #define PG8_STAGE(bufoff, gbase, voff) do { _Pragma("unroll") for (int _i = 0; _i < 2; ++_i) \
;         __builtin_amdgcn_global_load_lds((const unsigned*)((const char*)(gbase) + (voff)[_i]), (PG8_LAS unsigned*)(lds + (bufoff) + ldsw + _i * 8192), 16, 0, 0); } while (0)
; #define PG8_LDA(dst, b, h) do { _Pragma("unroll") for (int m = 0; m < 4; ++m) _Pragma("unroll") for (int k = 0; k < 2; ++k) dst[m][k] = *(const PG8_LAS bf16x8*)(lds + PG8_SA(b, h) + aoff + m * 2048 + k * 1024); } while (0)
; #define PG8_LDB(dst, b, h) do { _Pragma("unroll") for (int n = 0; n < 2; ++n) _Pragma("unroll") for (int k = 0; k < 2; ++k) dst[n][k] = *(const PG8_LAS bf16x8*)(lds + PG8_SB(b, h) + boff + n * 2048 + k * 1024); } while (0)
; #define PG8_WAIT_V(n) asm volatile("s_waitcnt vmcnt(" #n ")" ::: "memory")
; #define PG8_WAIT_L(n) asm volatile("s_waitcnt lgkmcnt(" #n ")" ::: "memory")
; #define PG8_BAR __builtin_amdgcn_s_barrier()
; #define PG8_SCHED __builtin_amdgcn_sched_barrier(0)
; template <class Epi, class Sched, bool ALIGN_EPI = false, bool SP2 = false>
; __device__ __forceinline__ void gemm_phase(PG8_LAS unsigned char* lds, const Gemm g, const Sched& S, const Epi& E) {
;     ...
;         const bool has_next = S.next(ui + 1, nxt);
;         const char* nA = has_next ? (const char*)g.A + (size_t)nxt.pm * tstep : cA; const char* nB = has_next ? (const char*)g.Bt + (size_t)nxt.pn * tstep : cB;
;         for (int t = 0; t < nt; t += 2) {
;             const bool last = (t == nt - 2);
;             const char* a1 = cA + (size_t)(t + 1) * kstep;
;             const char* a2 = last ? nA : cA + (size_t)(t + 2) * kstep; const char* b2 = last ? nB : cB + (size_t)(t + 2) * kstep;
;             const char* a3 = a2 + kstep; const char* b3 = b2 + kstep;
;             if (last && has_next) S.a_ready(nxt);
;             if constexpr (SP2) {
;             PG8_LDB(B0, 0, 0); PG8_LDB(B1, 0, 1); PG8_SCHED; PG8_LDA(At, 0, 0); PG8_STAGE(PG8_SA(1, 1), a1 + hstep, voffA);
;             PG8_WAIT_V(8); PG8_WAIT_L(0); PG8_BAR; PG8_MMA(0, 0, At, B0); PG8_MMA(0, 1, At, B1); PG8_BAR; PG8_SCHED;
;             PG8_LDA(At, 0, 1); PG8_STAGE(PG8_SB(0, 0), b2, voffB); PG8_STAGE(PG8_SB(0, 1), b2 + hstep, voffB); PG8_STAGE(PG8_SA(0, 0), a2, voffA);
;             PG8_WAIT_V(8); PG8_WAIT_L(0); PG8_BAR; PG8_MMA(1, 0, At, B0); PG8_MMA(1, 1, At, B1); PG8_BAR; PG8_SCHED;
.LBB0_330:
	s_ashr_i32 s45, s44, 31
	s_lshl_b64 s[46:47], s[44:45], 20
	s_add_u32 s46, s12, s46
	s_addc_u32 s47, s13, s47
	s_and_b64 s[48:49], s[40:41], exec
	s_cselect_b32 s45, s47, s75
	s_cselect_b32 s59, s46, s74
	s_ashr_i32 s43, s42, 31
	s_lshl_b64 s[48:49], s[42:43], 20
	s_add_u32 s48, s14, s48
	s_addc_u32 s49, s0, s49
	s_and_b64 s[78:79], s[40:41], exec
	s_cselect_b32 s43, s49, s77
	s_cselect_b32 s63, s48, s76
	s_add_u32 s74, s74, 0x80080
	s_addc_u32 s75, s75, 0
	s_add_u32 s71, s76, 0x100
	v_mov_b32_e32 v0, 0
	s_addc_u32 s80, s77, 0
	s_mov_b32 s81, -2
	s_add_u32 s68, s74, 0xfff80080
	s_addc_u32 s69, s75, -1
	s_add_i32 s82, 0, 0x10000
	s_cmp_eq_u32 s81, 28
	s_cselect_b32 s79, s45, s69
	s_cselect_b32 s78, s59, s68
	v_add_u32_e32 v140, s82, v143
	s_cselect_b32 s77, s43, s80
	s_cselect_b32 s76, s63, s71
	s_add_i32 s68, 0, 0x14000
	ds_read_b128 v[146:149], v140
	ds_read_b128 v[156:159], v140 offset:1024
	ds_read_b128 v[160:163], v140 offset:2048
	ds_read_b128 v[164:167], v140 offset:3072
	v_add_u32_e32 v140, s68, v143
	ds_read_b128 v[168:171], v140
	ds_read_b128 v[172:175], v140 offset:1024
	ds_read_b128 v[192:195], v140 offset:2048
	ds_read_b128 v[196:199], v140 offset:3072
	v_lshl_add_u64 v[140:141], s[74:75], 0, v[136:137]
	s_add_i32 m0, s16, 0xc000
	ds_read_b128 v[200:203], v145
	ds_read_b128 v[204:207], v145 offset:1024
	ds_read_b128 v[208:211], v145 offset:2048
	ds_read_b128 v[212:215], v145 offset:3072
	ds_read_b128 v[216:219], v145 offset:4096
	ds_read_b128 v[220:223], v145 offset:5120
	ds_read_b128 v[224:227], v145 offset:6144
	ds_read_b128 v[228:231], v145 offset:7168
	global_load_lds_dwordx4 v[140:141], off
	v_lshl_add_u64 v[140:141], s[74:75], 0, v[138:139]
	s_add_i32 m0, s16, 0xe000
	s_nop 0
	global_load_lds_dwordx4 v[140:141], off
	s_waitcnt vmcnt(8)
	s_waitcnt lgkmcnt(0)
	s_setprio 1
	s_barrier
	v_mfma_f32_16x16x32_bf16 v[116:119], v[146:149], v[200:203], 0
	v_mfma_f32_16x16x32_bf16 v[112:115], v[160:163], v[200:203], 0
	v_mfma_f32_16x16x32_bf16 v[104:107], v[146:149], v[208:211], 0
	v_mfma_f32_16x16x32_bf16 v[96:99], v[160:163], v[208:211], 0
	v_mfma_f32_16x16x32_bf16 v[88:91], v[146:149], v[216:219], 0
	v_mfma_f32_16x16x32_bf16 v[80:83], v[160:163], v[216:219], 0
	v_mfma_f32_16x16x32_bf16 v[72:75], v[146:149], v[224:227], 0
	v_mfma_f32_16x16x32_bf16 v[64:67], v[160:163], v[224:227], 0
	v_mfma_f32_16x16x32_bf16 v[116:119], v[156:159], v[204:207], v[116:119]
	v_mfma_f32_16x16x32_bf16 v[112:115], v[164:167], v[204:207], v[112:115]
	v_mfma_f32_16x16x32_bf16 v[104:107], v[156:159], v[212:215], v[104:107]
	v_mfma_f32_16x16x32_bf16 v[96:99], v[164:167], v[212:215], v[96:99]
	v_mfma_f32_16x16x32_bf16 v[88:91], v[156:159], v[220:223], v[88:91]
	v_mfma_f32_16x16x32_bf16 v[80:83], v[164:167], v[220:223], v[80:83]
	v_mfma_f32_16x16x32_bf16 v[72:75], v[156:159], v[228:231], v[72:75]
	v_mfma_f32_16x16x32_bf16 v[64:67], v[164:167], v[228:231], v[64:67]
	v_mfma_f32_16x16x32_bf16 v[124:127], v[168:171], v[200:203], 0
	v_mfma_f32_16x16x32_bf16 v[120:123], v[192:195], v[200:203], 0
	v_mfma_f32_16x16x32_bf16 v[108:111], v[168:171], v[208:211], 0
	v_mfma_f32_16x16x32_bf16 v[100:103], v[192:195], v[208:211], 0
	v_mfma_f32_16x16x32_bf16 v[92:95], v[168:171], v[216:219], 0
	v_mfma_f32_16x16x32_bf16 v[84:87], v[192:195], v[216:219], 0
	v_mfma_f32_16x16x32_bf16 v[76:79], v[168:171], v[224:227], 0
	v_mfma_f32_16x16x32_bf16 v[68:71], v[192:195], v[224:227], 0
	v_mfma_f32_16x16x32_bf16 v[124:127], v[172:175], v[204:207], v[124:127]
	v_mfma_f32_16x16x32_bf16 v[120:123], v[196:199], v[204:207], v[120:123]
	v_mfma_f32_16x16x32_bf16 v[108:111], v[172:175], v[212:215], v[108:111]
	v_mfma_f32_16x16x32_bf16 v[100:103], v[196:199], v[212:215], v[100:103]
	v_mfma_f32_16x16x32_bf16 v[92:95], v[172:175], v[220:223], v[92:95]
	v_mfma_f32_16x16x32_bf16 v[84:87], v[196:199], v[220:223], v[84:87]
	v_mfma_f32_16x16x32_bf16 v[76:79], v[172:175], v[228:231], v[76:79]
	v_mfma_f32_16x16x32_bf16 v[68:71], v[196:199], v[228:231], v[68:71]
	s_barrier
	s_setprio 0
	s_add_i32 s69, s82, s15
	v_lshl_add_u64 v[140:141], s[76:77], 0, v[152:153]
	s_mov_b32 m0, s69
	ds_read_b128 v[200:203], v145 offset:16384
	ds_read_b128 v[204:207], v145 offset:17408
	ds_read_b128 v[208:211], v145 offset:18432
	ds_read_b128 v[212:215], v145 offset:19456
	ds_read_b128 v[216:219], v145 offset:20480
	ds_read_b128 v[220:223], v145 offset:21504
	ds_read_b128 v[224:227], v145 offset:22528
	ds_read_b128 v[228:231], v145 offset:23552
	global_load_lds_dwordx4 v[140:141], off
	s_add_i32 m0, s69, 0x2000
	s_add_u32 s82, s76, 0x80000
	v_lshl_add_u64 v[150:151], s[76:77], 0, v[128:129]
	s_addc_u32 s83, s77, 0
	s_add_i32 s68, s68, s15
	global_load_lds_dwordx4 v[150:151], off
	v_lshl_add_u64 v[182:183], s[82:83], 0, v[152:153]
	s_mov_b32 m0, s68
	v_lshl_add_u64 v[184:185], s[78:79], 0, v[130:131]
	global_load_lds_dwordx4 v[182:183], off
	v_lshl_add_u64 v[182:183], s[82:83], 0, v[128:129]
	s_add_i32 m0, s68, 0x2000
	s_nop 0
	global_load_lds_dwordx4 v[182:183], off
	v_lshl_add_u64 v[182:183], s[78:79], 0, v[132:133]
	s_mov_b32 m0, s16
	s_nop 0
	global_load_lds_dwordx4 v[182:183], off
	s_mov_b32 m0, s17
	s_nop 0
	global_load_lds_dwordx4 v[184:185], off
	s_waitcnt vmcnt(8)
	s_waitcnt lgkmcnt(0)
	s_setprio 1
	s_barrier
; #define PG8_STAGE(bufoff, gbase, voff) do { _Pragma("unroll") for (int _i = 0; _i < 2; ++_i) \
;         __builtin_amdgcn_global_load_lds((const unsigned*)((const char*)(gbase) + (voff)[_i]), (PG8_LAS unsigned*)(lds + (bufoff) + ldsw + _i * 8192), 16, 0, 0); } while (0)
; #define PG8_LDA(dst, b, h) do { _Pragma("unroll") for (int m = 0; m < 4; ++m) _Pragma("unroll") for (int k = 0; k < 2; ++k) dst[m][k] = *(const PG8_LAS bf16x8*)(lds + PG8_SA(b, h) + aoff + m * 2048 + k * 1024); } while (0)
; #define PG8_LDB(dst, b, h) do { _Pragma("unroll") for (int n = 0; n < 2; ++n) _Pragma("unroll") for (int k = 0; k < 2; ++k) dst[n][k] = *(const PG8_LAS bf16x8*)(lds + PG8_SB(b, h) + boff + n * 2048 + k * 1024); } while (0)
; #define PG8_MMA(ai, bj, At, Bt) do { __builtin_amdgcn_s_setprio(1); _Pragma("unroll") for (int m = 0; m < 4; ++m) _Pragma("unroll") for (int n = 0; n < 2; ++n) _Pragma("unroll") for (int k = 0; k < 2; ++k) \
;         acc[ai][bj][m][n] = __builtin_amdgcn_mfma_f32_16x16x32_bf16(Bt[n][k], At[m][k], acc[ai][bj][m][n], 0, 0, 0); __builtin_amdgcn_s_setprio(0); } while (0)
; #define PG8_WAIT_V(n) asm volatile("s_waitcnt vmcnt(" #n ")" ::: "memory")
; #define PG8_WAIT_L(n) asm volatile("s_waitcnt lgkmcnt(" #n ")" ::: "memory")
; #define PG8_BAR __builtin_amdgcn_s_barrier()
; #define PG8_SCHED __builtin_amdgcn_sched_barrier(0)
; template <class Epi, class Sched, bool ALIGN_EPI = false, bool SP2 = false>
; __device__ __forceinline__ void gemm_phase(PG8_LAS unsigned char* lds, const Gemm g, const Sched& S, const Epi& E) {
;     ...
;             PG8_WAIT_V(8); PG8_WAIT_L(0); PG8_BAR; PG8_MMA(1, 0, At, B0); PG8_MMA(1, 1, At, B1); PG8_BAR; PG8_SCHED;
;             PG8_LDB(B0, 1, 0); PG8_LDB(B1, 1, 1); PG8_SCHED; PG8_LDA(At, 1, 0); PG8_STAGE(PG8_SA(0, 1), a2 + hstep, voffA);
;             PG8_WAIT_V(8); PG8_WAIT_L(0); PG8_BAR; PG8_MMA(0, 0, At, B0); PG8_MMA(0, 1, At, B1); PG8_BAR; PG8_SCHED;
;             PG8_LDA(At, 1, 1); PG8_STAGE(PG8_SB(1, 0), b3, voffB); PG8_STAGE(PG8_SB(1, 1), b3 + hstep, voffB); PG8_STAGE(PG8_SA(1, 0), a3, voffA);
	v_mfma_f32_16x16x32_bf16 v[56:59], v[146:149], v[200:203], 0
	v_mfma_f32_16x16x32_bf16 v[48:51], v[160:163], v[200:203], 0
	v_mfma_f32_16x16x32_bf16 v[40:43], v[146:149], v[208:211], 0
	v_mfma_f32_16x16x32_bf16 v[32:35], v[160:163], v[208:211], 0
	v_mfma_f32_16x16x32_bf16 v[24:27], v[146:149], v[216:219], 0
	v_mfma_f32_16x16x32_bf16 v[16:19], v[160:163], v[216:219], 0
	v_mfma_f32_16x16x32_bf16 v[8:11], v[146:149], v[224:227], 0
	v_mfma_f32_16x16x32_bf16 v[4:7], v[160:163], v[224:227], 0
	v_mfma_f32_16x16x32_bf16 v[56:59], v[156:159], v[204:207], v[56:59]
	v_mfma_f32_16x16x32_bf16 v[48:51], v[164:167], v[204:207], v[48:51]
	v_mfma_f32_16x16x32_bf16 v[40:43], v[156:159], v[212:215], v[40:43]
	v_mfma_f32_16x16x32_bf16 v[32:35], v[164:167], v[212:215], v[32:35]
	v_mfma_f32_16x16x32_bf16 v[24:27], v[156:159], v[220:223], v[24:27]
	v_mfma_f32_16x16x32_bf16 v[16:19], v[164:167], v[220:223], v[16:19]
	v_mfma_f32_16x16x32_bf16 v[8:11], v[156:159], v[228:231], v[8:11]
	v_mfma_f32_16x16x32_bf16 v[4:7], v[164:167], v[228:231], v[4:7]
	v_mfma_f32_16x16x32_bf16 v[60:63], v[168:171], v[200:203], 0
	v_mfma_f32_16x16x32_bf16 v[52:55], v[192:195], v[200:203], 0
	v_mfma_f32_16x16x32_bf16 v[44:47], v[168:171], v[208:211], 0
	v_mfma_f32_16x16x32_bf16 v[36:39], v[192:195], v[208:211], 0
	v_mfma_f32_16x16x32_bf16 v[28:31], v[168:171], v[216:219], 0
	v_mfma_f32_16x16x32_bf16 v[20:23], v[192:195], v[216:219], 0
	v_mfma_f32_16x16x32_bf16 v[12:15], v[168:171], v[224:227], 0
	v_mfma_f32_16x16x32_bf16 v[0:3], v[192:195], v[224:227], 0
	v_mfma_f32_16x16x32_bf16 v[60:63], v[172:175], v[204:207], v[60:63]
	v_mfma_f32_16x16x32_bf16 v[52:55], v[196:199], v[204:207], v[52:55]
	v_mfma_f32_16x16x32_bf16 v[44:47], v[172:175], v[212:215], v[44:47]
	v_mfma_f32_16x16x32_bf16 v[36:39], v[196:199], v[212:215], v[36:39]
	v_mfma_f32_16x16x32_bf16 v[28:31], v[172:175], v[220:223], v[28:31]
	v_mfma_f32_16x16x32_bf16 v[20:23], v[196:199], v[220:223], v[20:23]
	v_mfma_f32_16x16x32_bf16 v[12:15], v[172:175], v[228:231], v[12:15]
	v_mfma_f32_16x16x32_bf16 v[0:3], v[196:199], v[228:231], v[0:3]
	s_barrier
	s_setprio 0
	v_add_u32_e32 v155, s93, v143
	s_add_i32 s68, 0, 0x1c000
	ds_read_b128 v[146:149], v155
	ds_read_b128 v[156:159], v155 offset:1024
	ds_read_b128 v[160:163], v155 offset:2048
	ds_read_b128 v[164:167], v155 offset:3072
	v_add_u32_e32 v155, s68, v143
	ds_read_b128 v[168:171], v155
	ds_read_b128 v[172:175], v155 offset:1024
	ds_read_b128 v[192:195], v155 offset:2048
	ds_read_b128 v[196:199], v155 offset:3072
	s_add_u32 s78, s78, 0x80000
	s_addc_u32 s79, s79, 0
	s_mov_b32 m0, s22
	v_lshl_add_u64 v[188:189], s[78:79], 0, v[132:133]
	ds_read_b128 v[200:203], v145 offset:32768
	ds_read_b128 v[204:207], v145 offset:33792
	ds_read_b128 v[208:211], v145 offset:34816
	ds_read_b128 v[212:215], v145 offset:35840
	ds_read_b128 v[216:219], v145 offset:36864
	ds_read_b128 v[220:223], v145 offset:37888
	ds_read_b128 v[224:227], v145 offset:38912
	ds_read_b128 v[228:231], v145 offset:39936
	global_load_lds_dwordx4 v[188:189], off
	v_lshl_add_u64 v[188:189], s[78:79], 0, v[130:131]
	s_mov_b32 m0, s23
	s_nop 0
	global_load_lds_dwordx4 v[188:189], off
	s_waitcnt vmcnt(8)
	s_waitcnt lgkmcnt(0)
	s_setprio 1
	s_barrier
	v_mfma_f32_16x16x32_bf16 v[116:119], v[146:149], v[200:203], v[116:119]
	v_mfma_f32_16x16x32_bf16 v[112:115], v[160:163], v[200:203], v[112:115]
	v_mfma_f32_16x16x32_bf16 v[104:107], v[146:149], v[208:211], v[104:107]
	v_mfma_f32_16x16x32_bf16 v[96:99], v[160:163], v[208:211], v[96:99]
	v_mfma_f32_16x16x32_bf16 v[88:91], v[146:149], v[216:219], v[88:91]
	v_mfma_f32_16x16x32_bf16 v[80:83], v[160:163], v[216:219], v[80:83]
	v_mfma_f32_16x16x32_bf16 v[72:75], v[146:149], v[224:227], v[72:75]
	v_mfma_f32_16x16x32_bf16 v[64:67], v[160:163], v[224:227], v[64:67]
	v_mfma_f32_16x16x32_bf16 v[116:119], v[156:159], v[204:207], v[116:119]
	v_mfma_f32_16x16x32_bf16 v[112:115], v[164:167], v[204:207], v[112:115]
	v_mfma_f32_16x16x32_bf16 v[104:107], v[156:159], v[212:215], v[104:107]
	v_mfma_f32_16x16x32_bf16 v[96:99], v[164:167], v[212:215], v[96:99]
	v_mfma_f32_16x16x32_bf16 v[88:91], v[156:159], v[220:223], v[88:91]
	v_mfma_f32_16x16x32_bf16 v[80:83], v[164:167], v[220:223], v[80:83]
	v_mfma_f32_16x16x32_bf16 v[72:75], v[156:159], v[228:231], v[72:75]
	v_mfma_f32_16x16x32_bf16 v[64:67], v[164:167], v[228:231], v[64:67]
	v_mfma_f32_16x16x32_bf16 v[124:127], v[168:171], v[200:203], v[124:127]
	v_mfma_f32_16x16x32_bf16 v[120:123], v[192:195], v[200:203], v[120:123]
	v_mfma_f32_16x16x32_bf16 v[108:111], v[168:171], v[208:211], v[108:111]
	v_mfma_f32_16x16x32_bf16 v[100:103], v[192:195], v[208:211], v[100:103]
	v_mfma_f32_16x16x32_bf16 v[92:95], v[168:171], v[216:219], v[92:95]
	v_mfma_f32_16x16x32_bf16 v[84:87], v[192:195], v[216:219], v[84:87]
	v_mfma_f32_16x16x32_bf16 v[76:79], v[168:171], v[224:227], v[76:79]
	v_mfma_f32_16x16x32_bf16 v[68:71], v[192:195], v[224:227], v[68:71]
	v_mfma_f32_16x16x32_bf16 v[124:127], v[172:175], v[204:207], v[124:127]
	v_mfma_f32_16x16x32_bf16 v[120:123], v[196:199], v[204:207], v[120:123]
	v_mfma_f32_16x16x32_bf16 v[108:111], v[172:175], v[212:215], v[108:111]
	v_mfma_f32_16x16x32_bf16 v[100:103], v[196:199], v[212:215], v[100:103]
	v_mfma_f32_16x16x32_bf16 v[92:95], v[172:175], v[220:223], v[92:95]
	v_mfma_f32_16x16x32_bf16 v[84:87], v[196:199], v[220:223], v[84:87]
	v_mfma_f32_16x16x32_bf16 v[76:79], v[172:175], v[228:231], v[76:79]
	v_mfma_f32_16x16x32_bf16 v[68:71], v[196:199], v[228:231], v[68:71]
	s_barrier
; #define PG8_STAGE(bufoff, gbase, voff) do { _Pragma("unroll") for (int _i = 0; _i < 2; ++_i) \
;         __builtin_amdgcn_global_load_lds((const unsigned*)((const char*)(gbase) + (voff)[_i]), (PG8_LAS unsigned*)(lds + (bufoff) + ldsw + _i * 8192), 16, 0, 0); } while (0)
; #define PG8_LDA(dst, b, h) do { _Pragma("unroll") for (int m = 0; m < 4; ++m) _Pragma("unroll") for (int k = 0; k < 2; ++k) dst[m][k] = *(const PG8_LAS bf16x8*)(lds + PG8_SA(b, h) + aoff + m * 2048 + k * 1024); } while (0)
; #define PG8_LDB(dst, b, h) do { _Pragma("unroll") for (int n = 0; n < 2; ++n) _Pragma("unroll") for (int k = 0; k < 2; ++k) dst[n][k] = *(const PG8_LAS bf16x8*)(lds + PG8_SB(b, h) + boff + n * 2048 + k * 1024); } while (0)
; template <class Epi, class Sched, bool ALIGN_EPI = false, bool SP2 = false>
; __device__ __forceinline__ void gemm_phase(PG8_LAS unsigned char* lds, const Gemm g, const Sched& S, const Epi& E) {
;     ...
;         for (int t = 0; t < nt; t += 2) {
;             const bool last = (t == nt - 2);
;             const char* a1 = cA + (size_t)(t + 1) * kstep;
;             const char* a2 = last ? nA : cA + (size_t)(t + 2) * kstep; const char* b2 = last ? nB : cB + (size_t)(t + 2) * kstep;
;             const char* a3 = a2 + kstep; const char* b3 = b2 + kstep;
;             if (last && has_next) S.a_ready(nxt);
;             if constexpr (SP2) {
;             PG8_LDB(B0, 0, 0); PG8_LDB(B1, 0, 1); PG8_SCHED; PG8_LDA(At, 0, 0); PG8_STAGE(PG8_SA(1, 1), a1 + hstep, voffA);
;             PG8_WAIT_V(8); PG8_WAIT_L(0); PG8_BAR; PG8_MMA(0, 0, At, B0); PG8_MMA(0, 1, At, B1); PG8_BAR; PG8_SCHED;
;             PG8_LDA(At, 0, 1); PG8_STAGE(PG8_SB(0, 0), b2, voffB); PG8_STAGE(PG8_SB(0, 1), b2 + hstep, voffB); PG8_STAGE(PG8_SA(0, 0), a2, voffA);
;             PG8_WAIT_V(8); PG8_WAIT_L(0); PG8_BAR; PG8_MMA(1, 0, At, B0); PG8_MMA(1, 1, At, B1); PG8_BAR; PG8_SCHED;
;             PG8_LDB(B0, 1, 0); PG8_LDB(B1, 1, 1); PG8_SCHED; PG8_LDA(At, 1, 0); PG8_STAGE(PG8_SA(0, 1), a2 + hstep, voffA);
;             PG8_WAIT_V(8); PG8_WAIT_L(0); PG8_BAR; PG8_MMA(0, 0, At, B0); PG8_MMA(0, 1, At, B1); PG8_BAR; PG8_SCHED;
;             PG8_LDA(At, 1, 1); PG8_STAGE(PG8_SB(1, 0), b3, voffB); PG8_STAGE(PG8_SB(1, 1), b3 + hstep, voffB); PG8_STAGE(PG8_SA(1, 0), a3, voffA);
;             PG8_WAIT_V(8); PG8_WAIT_L(0); PG8_BAR; PG8_MMA(1, 0, At, B0); PG8_MMA(1, 1, At, B1); PG8_BAR; PG8_SCHED;
	s_setprio 0
	s_add_i32 s69, s93, s15
	v_lshl_add_u64 v[140:141], v[140:141], 0, s[18:19]
	s_mov_b32 m0, s69
	ds_read_b128 v[200:203], v145 offset:49152
	ds_read_b128 v[204:207], v145 offset:50176
	ds_read_b128 v[208:211], v145 offset:51200
	ds_read_b128 v[212:215], v145 offset:52224
	ds_read_b128 v[216:219], v145 offset:53248
	ds_read_b128 v[220:223], v145 offset:54272
	ds_read_b128 v[224:227], v145 offset:55296
	ds_read_b128 v[228:231], v145 offset:56320
	global_load_lds_dwordx4 v[140:141], off
	s_add_i32 m0, s69, 0x2000
	s_add_u32 s76, s76, 0x80080
	v_lshl_add_u64 v[140:141], v[150:151], 0, s[18:19]
	s_addc_u32 s77, s77, 0
	s_add_i32 s68, s68, s15
	global_load_lds_dwordx4 v[140:141], off
	v_lshl_add_u64 v[140:141], s[76:77], 0, v[152:153]
	s_mov_b32 m0, s68
	s_nop 0
	global_load_lds_dwordx4 v[140:141], off
	v_lshl_add_u64 v[140:141], s[76:77], 0, v[128:129]
	s_add_i32 m0, s68, 0x2000
	s_nop 0
	global_load_lds_dwordx4 v[140:141], off
	v_lshl_add_u64 v[140:141], v[182:183], 0, s[18:19]
	s_mov_b32 m0, s26
	s_nop 0
	global_load_lds_dwordx4 v[140:141], off
	v_lshl_add_u64 v[140:141], v[184:185], 0, s[18:19]
	s_mov_b32 m0, s34
	s_nop 0
	global_load_lds_dwordx4 v[140:141], off
	s_waitcnt vmcnt(8)
	s_waitcnt lgkmcnt(0)
	s_setprio 1
	s_barrier
	v_mfma_f32_16x16x32_bf16 v[56:59], v[146:149], v[200:203], v[56:59]
	v_mfma_f32_16x16x32_bf16 v[48:51], v[160:163], v[200:203], v[48:51]
	v_mfma_f32_16x16x32_bf16 v[40:43], v[146:149], v[208:211], v[40:43]
	v_mfma_f32_16x16x32_bf16 v[32:35], v[160:163], v[208:211], v[32:35]
	v_mfma_f32_16x16x32_bf16 v[24:27], v[146:149], v[216:219], v[24:27]
	v_mfma_f32_16x16x32_bf16 v[16:19], v[160:163], v[216:219], v[16:19]
	v_mfma_f32_16x16x32_bf16 v[8:11], v[146:149], v[224:227], v[8:11]
	v_mfma_f32_16x16x32_bf16 v[4:7], v[160:163], v[224:227], v[4:7]
	v_mfma_f32_16x16x32_bf16 v[56:59], v[156:159], v[204:207], v[56:59]
	v_mfma_f32_16x16x32_bf16 v[48:51], v[164:167], v[204:207], v[48:51]
	v_mfma_f32_16x16x32_bf16 v[40:43], v[156:159], v[212:215], v[40:43]
	v_mfma_f32_16x16x32_bf16 v[32:35], v[164:167], v[212:215], v[32:35]
	v_mfma_f32_16x16x32_bf16 v[24:27], v[156:159], v[220:223], v[24:27]
	v_mfma_f32_16x16x32_bf16 v[16:19], v[164:167], v[220:223], v[16:19]
	v_mfma_f32_16x16x32_bf16 v[8:11], v[156:159], v[228:231], v[8:11]
	v_mfma_f32_16x16x32_bf16 v[4:7], v[164:167], v[228:231], v[4:7]
	v_mfma_f32_16x16x32_bf16 v[60:63], v[168:171], v[200:203], v[60:63]
	v_mfma_f32_16x16x32_bf16 v[52:55], v[192:195], v[200:203], v[52:55]
	v_mfma_f32_16x16x32_bf16 v[44:47], v[168:171], v[208:211], v[44:47]
	v_mfma_f32_16x16x32_bf16 v[36:39], v[192:195], v[208:211], v[36:39]
	v_mfma_f32_16x16x32_bf16 v[28:31], v[168:171], v[216:219], v[28:31]
	v_mfma_f32_16x16x32_bf16 v[20:23], v[192:195], v[216:219], v[20:23]
	v_mfma_f32_16x16x32_bf16 v[12:15], v[168:171], v[224:227], v[12:15]
	v_mfma_f32_16x16x32_bf16 v[0:3], v[192:195], v[224:227], v[0:3]
	v_mfma_f32_16x16x32_bf16 v[60:63], v[172:175], v[204:207], v[60:63]
	v_mfma_f32_16x16x32_bf16 v[52:55], v[196:199], v[204:207], v[52:55]
	v_mfma_f32_16x16x32_bf16 v[44:47], v[172:175], v[212:215], v[44:47]
	v_mfma_f32_16x16x32_bf16 v[36:39], v[196:199], v[212:215], v[36:39]
	v_mfma_f32_16x16x32_bf16 v[28:31], v[172:175], v[220:223], v[28:31]
	v_mfma_f32_16x16x32_bf16 v[20:23], v[196:199], v[220:223], v[20:23]
	v_mfma_f32_16x16x32_bf16 v[12:15], v[172:175], v[228:231], v[12:15]
	v_mfma_f32_16x16x32_bf16 v[0:3], v[196:199], v[228:231], v[0:3]
	s_barrier
	s_setprio 0
	s_add_i32 s81, s81, 2
	s_add_u32 s74, s74, 0x100
	s_addc_u32 s75, s75, 0
	s_add_u32 s71, s71, 0x100
	s_addc_u32 s80, s80, 0
	s_cmp_gt_u32 s81, 29
	s_cbranch_scc1 .Lpeel_exit_331
